# P4 tail weight transposes replaced by LDS-free 32x64-tile routine with 3 tiles in flight per wave (same f32 mul + RNE bf16 cvt)
# speedup vs baseline: 1.0320x; 1.0220x over previous
.LBB0_687:
	v_readlane_b32 s52, v249, 45
	v_mov_b32_e32 v68, v184
	s_and_b64 vcc, exec, s[18:19]
	v_readlane_b32 s53, v249, 46
	s_waitcnt vmcnt(0) lgkmcnt(0)
	s_barrier
	s_cbranch_vccz .Ltp4_spread
	v_writelane_b32 v251, s0, 0
	v_writelane_b32 v251, s1, 1
	v_writelane_b32 v251, s2, 2
	v_writelane_b32 v251, s3, 3
	v_writelane_b32 v251, s4, 4
	v_writelane_b32 v251, s5, 5
	v_writelane_b32 v251, s6, 6
	v_writelane_b32 v251, s7, 7
	v_writelane_b32 v251, s8, 8
	v_writelane_b32 v251, s9, 9
	v_writelane_b32 v251, s10, 10
	v_writelane_b32 v251, s11, 11
	v_writelane_b32 v251, s12, 12
	v_writelane_b32 v251, s13, 13
	v_writelane_b32 v251, s14, 14
	v_writelane_b32 v251, s15, 15
	v_writelane_b32 v251, s16, 16
	v_writelane_b32 v251, s17, 17
	v_writelane_b32 v251, s18, 18
	v_writelane_b32 v251, s19, 19
	s_mov_b32 s0, s30
	v_readlane_b32 s1, v248, 34
	s_branch .Ltp4_go
.Ltp4_spread:
	v_writelane_b32 v251, s0, 0
	v_writelane_b32 v251, s1, 1
	v_writelane_b32 v251, s2, 2
	v_writelane_b32 v251, s3, 3
	v_writelane_b32 v251, s4, 4
	v_writelane_b32 v251, s5, 5
	v_writelane_b32 v251, s6, 6
	v_writelane_b32 v251, s7, 7
	v_writelane_b32 v251, s8, 8
	v_writelane_b32 v251, s9, 9
	v_writelane_b32 v251, s10, 10
	v_writelane_b32 v251, s11, 11
	v_writelane_b32 v251, s12, 12
	v_writelane_b32 v251, s13, 13
	v_writelane_b32 v251, s14, 14
	v_writelane_b32 v251, s15, 15
	v_writelane_b32 v251, s16, 16
	v_writelane_b32 v251, s17, 17
	v_writelane_b32 v251, s18, 18
	v_writelane_b32 v251, s19, 19
	s_cmp_lt_i32 s2, s62
	s_cbranch_scc1 .Ltp4_done
	s_sub_i32 s0, s2, s62
	s_lshl_b32 s0, s0, 3
	s_add_i32 s0, s0, s90
	s_sub_i32 s1, s84, s62
	s_lshl_b32 s1, s1, 3
.Ltp4_go:
	v_and_b32_e32 v2, 15, v184
	v_lshrrev_b32_e32 v1, 4, v184
	v_lshlrev_b32_e32 v0, 4, v2
	v_lshlrev_b32_e32 v2, 2, v2
	v_lshlrev_b32_e32 v3, 5, v1
	v_lshlrev_b32_e32 v6, 4, v1
.Ltp4_loop:
	s_cmp_lt_u32 s0, 4736
	s_cbranch_scc0 .Ltp4_done
	s_add_u32 s2, s0, s1
	s_cmp_lt_u32 s2, 4736
	s_cselect_b32 s2, s2, s0
	s_add_u32 s3, s0, s1
	s_add_u32 s3, s3, s1
	s_cmp_lt_u32 s3, 4736
	s_cselect_b32 s3, s3, s0
	s_cmp_lt_u32 s0, 2816
	s_cbranch_scc0 .Ltp41_hi
	s_cmp_lt_u32 s0, 1408
	s_cselect_b32 s15, 0, 1408
	s_cselect_b32 s19, 0, 1
	s_sub_u32 s15, s0, s15
	s_mul_hi_u32 s16, s15, 0x5d1745e
	s_mul_i32 s17, s16, 44
	s_sub_u32 s17, s15, s17
	s_cmp_eq_u32 s19, 0
	s_cbranch_scc0 .Ltp41_wu
	v_readlane_b32 s4, v248, 5
	v_readlane_b32 s5, v248, 6
	s_branch .Ltp41_wgu
.Ltp41_wu:
	v_readlane_b32 s4, v248, 7
	v_readlane_b32 s5, v248, 8
.Ltp41_wgu:
	v_readlane_b32 s12, v248, 3
	v_readlane_b32 s13, v248, 4
	s_movk_i32 s6, 0x2c00
	s_mul_i32 s18, s16, 0x58000
	s_lshl_b32 s15, s17, 8
	s_add_u32 s18, s18, s15
	s_nop 0
	s_add_u32 s4, s4, s18
	s_addc_u32 s5, s5, 0
	s_lshl_b32 s15, s16, 7
	s_add_u32 s12, s12, s15
	s_addc_u32 s13, s13, 0
	s_branch .Ltp41_end
.Ltp41_hi:
	s_cmp_lt_u32 s0, 4224
	s_mov_b32 s15, 4224
	s_cselect_b32 s15, 2816, s15
	s_cselect_b32 s19, 0, 1
	s_sub_u32 s15, s0, s15
	s_lshr_b32 s16, s15, 4
	s_and_b32 s17, s15, 15
	s_cmp_eq_u32 s19, 0
	s_cbranch_scc0 .Ltp41_wpg
	v_readlane_b32 s4, v249, 49
	v_readlane_b32 s5, v249, 50
	v_readlane_b32 s12, v248, 3
	v_readlane_b32 s13, v248, 4
	s_mov_b32 s15, 0
	s_branch .Ltp41_wdpg
.Ltp41_wpg:
	v_readlane_b32 s4, v249, 53
	v_readlane_b32 s5, v249, 54
	v_readlane_b32 s12, v249, 51
	v_readlane_b32 s13, v249, 52
	s_lshl_b32 s15, s16, 7
.Ltp41_wdpg:
	s_movk_i32 s6, 0x1000
	s_lshl_b32 s18, s16, 17
	s_lshl_b32 s19, s17, 8
	s_add_u32 s18, s18, s19
	s_add_u32 s4, s4, s18
	s_addc_u32 s5, s5, 0
	s_add_u32 s12, s12, s15
	s_addc_u32 s13, s13, 0
.Ltp41_end:
	s_lshl_b32 s7, s6, 3
	s_nop 0
	v_mad_u32_u24 v4, v1, s7, v0
	s_nop 3
	global_load_dwordx4 v[16:19], v4, s[4:5]
	s_add_u32 s4, s4, s6
	s_addc_u32 s5, s5, 0
	global_load_dwordx4 v[20:23], v4, s[4:5]
	s_add_u32 s4, s4, s6
	s_addc_u32 s5, s5, 0
	global_load_dwordx4 v[24:27], v4, s[4:5]
	s_add_u32 s4, s4, s6
	s_addc_u32 s5, s5, 0
	global_load_dwordx4 v[28:31], v4, s[4:5]
	s_add_u32 s4, s4, s6
	s_addc_u32 s5, s5, 0
	global_load_dwordx4 v[32:35], v4, s[4:5]
	s_add_u32 s4, s4, s6
	s_addc_u32 s5, s5, 0
	global_load_dwordx4 v[36:39], v4, s[4:5]
	s_add_u32 s4, s4, s6
	s_addc_u32 s5, s5, 0
	global_load_dwordx4 v[40:43], v4, s[4:5]
	s_add_u32 s4, s4, s6
	s_addc_u32 s5, s5, 0
	global_load_dwordx4 v[44:47], v4, s[4:5]
	global_load_dwordx4 v[48:51], v3, s[12:13]
	global_load_dwordx4 v[52:55], v3, s[12:13] offset:16
	s_cmp_lt_u32 s2, 2816
	s_cbranch_scc0 .Ltp42_hi
	s_cmp_lt_u32 s2, 1408
	s_cselect_b32 s15, 0, 1408
	s_cselect_b32 s19, 0, 1
	s_sub_u32 s15, s2, s15
	s_mul_hi_u32 s16, s15, 0x5d1745e
	s_mul_i32 s17, s16, 44
	s_sub_u32 s17, s15, s17
	s_cmp_eq_u32 s19, 0
	s_cbranch_scc0 .Ltp42_wu
	v_readlane_b32 s4, v248, 5
	v_readlane_b32 s5, v248, 6
	s_branch .Ltp42_wgu

.Ltp42_hi:
	s_cmp_lt_u32 s2, 4224
	s_mov_b32 s15, 4224
	s_cselect_b32 s15, 2816, s15
	s_cselect_b32 s19, 0, 1
	s_sub_u32 s15, s2, s15
	s_lshr_b32 s16, s15, 4
	s_and_b32 s17, s15, 15
	s_cmp_eq_u32 s19, 0
	s_cbranch_scc0 .Ltp42_wpg
	v_readlane_b32 s4, v249, 49
	v_readlane_b32 s5, v249, 50
	v_readlane_b32 s12, v248, 3
	v_readlane_b32 s13, v248, 4
	s_mov_b32 s15, 0
	s_branch .Ltp42_wdpg

.Ltp42_end:
	s_lshl_b32 s7, s6, 3
	s_nop 0
	v_mad_u32_u24 v4, v1, s7, v0
	s_nop 3
	global_load_dwordx4 v[56:59], v4, s[4:5]
	s_add_u32 s4, s4, s6
	s_addc_u32 s5, s5, 0
	global_load_dwordx4 v[60:63], v4, s[4:5]
	s_add_u32 s4, s4, s6
	s_addc_u32 s5, s5, 0
	global_load_dwordx4 v[64:67], v4, s[4:5]
	s_add_u32 s4, s4, s6
	s_addc_u32 s5, s5, 0
	global_load_dwordx4 v[68:71], v4, s[4:5]
	s_add_u32 s4, s4, s6
	s_addc_u32 s5, s5, 0
	global_load_dwordx4 v[72:75], v4, s[4:5]
	s_add_u32 s4, s4, s6
	s_addc_u32 s5, s5, 0
	global_load_dwordx4 v[76:79], v4, s[4:5]
	s_add_u32 s4, s4, s6
	s_addc_u32 s5, s5, 0
	global_load_dwordx4 v[80:83], v4, s[4:5]
	s_add_u32 s4, s4, s6
	s_addc_u32 s5, s5, 0
	global_load_dwordx4 v[84:87], v4, s[4:5]
	global_load_dwordx4 v[88:91], v3, s[12:13]
	global_load_dwordx4 v[92:95], v3, s[12:13] offset:16
	s_cmp_lt_u32 s3, 2816
	s_cbranch_scc0 .Ltp43_hi
	s_cmp_lt_u32 s3, 1408
	s_cselect_b32 s15, 0, 1408
	s_cselect_b32 s19, 0, 1
	s_sub_u32 s15, s3, s15
	s_mul_hi_u32 s16, s15, 0x5d1745e
	s_mul_i32 s17, s16, 44
	s_sub_u32 s17, s15, s17
	s_cmp_eq_u32 s19, 0
	s_cbranch_scc0 .Ltp43_wu
	v_readlane_b32 s4, v248, 5
	v_readlane_b32 s5, v248, 6
	s_branch .Ltp43_wgu

.Ltp43_hi:
	s_cmp_lt_u32 s3, 4224
	s_mov_b32 s15, 4224
	s_cselect_b32 s15, 2816, s15
	s_cselect_b32 s19, 0, 1
	s_sub_u32 s15, s3, s15
	s_lshr_b32 s16, s15, 4
	s_and_b32 s17, s15, 15
	s_cmp_eq_u32 s19, 0
	s_cbranch_scc0 .Ltp43_wpg
	v_readlane_b32 s4, v249, 49
	v_readlane_b32 s5, v249, 50
	v_readlane_b32 s12, v248, 3
	v_readlane_b32 s13, v248, 4
	s_mov_b32 s15, 0
	s_branch .Ltp43_wdpg

.Ltp43_end:
	s_lshl_b32 s7, s6, 3
	s_nop 0
	v_mad_u32_u24 v4, v1, s7, v0
	s_nop 3
	global_load_dwordx4 v[96:99], v4, s[4:5]
	s_add_u32 s4, s4, s6
	s_addc_u32 s5, s5, 0
	global_load_dwordx4 v[100:103], v4, s[4:5]
	s_add_u32 s4, s4, s6
	s_addc_u32 s5, s5, 0
	global_load_dwordx4 v[104:107], v4, s[4:5]
	s_add_u32 s4, s4, s6
	s_addc_u32 s5, s5, 0
	global_load_dwordx4 v[108:111], v4, s[4:5]
	s_add_u32 s4, s4, s6
	s_addc_u32 s5, s5, 0
	global_load_dwordx4 v[112:115], v4, s[4:5]
	s_add_u32 s4, s4, s6
	s_addc_u32 s5, s5, 0
	global_load_dwordx4 v[116:119], v4, s[4:5]
	s_add_u32 s4, s4, s6
	s_addc_u32 s5, s5, 0
	global_load_dwordx4 v[120:123], v4, s[4:5]
	s_add_u32 s4, s4, s6
	s_addc_u32 s5, s5, 0
	global_load_dwordx4 v[124:127], v4, s[4:5]
	global_load_dwordx4 v[128:131], v3, s[12:13]
	global_load_dwordx4 v[132:135], v3, s[12:13] offset:16
	s_waitcnt vmcnt(20)
	s_cmp_lt_u32 s0, 2816
	s_cbranch_scc0 .Ltp44_hi
	s_cmp_lt_u32 s0, 1408
	s_cselect_b32 s15, 0, 1408
	s_cselect_b32 s19, 0, 1
	s_sub_u32 s15, s0, s15
	s_mul_hi_u32 s16, s15, 0x5d1745e
	s_mul_i32 s17, s16, 44
	s_sub_u32 s17, s15, s17
	s_lshr_b32 s15, s17, 1
	s_lshl_b32 s15, s15, 8
	s_and_b32 s18, s17, 1
	s_lshl_b32 s18, s18, 6
	s_add_u32 s15, s15, s18
	s_lshl_b32 s18, s19, 7
	s_add_u32 s15, s15, s18
	s_lshl_b32 s15, s15, 11
	s_lshl_b32 s18, s16, 6
	s_add_u32 s15, s15, s18
	s_add_u32 s15, s15, 0x700000
	s_add_u32 s8, s24, s15
	s_addc_u32 s9, s25, 0
	s_movk_i32 s10, 0x800
	s_mov_b32 s14, 1
	s_branch .Ltp44_end
.Ltp44_hi:
	s_cmp_lt_u32 s0, 4224
	s_mov_b32 s15, 4224
	s_cselect_b32 s15, 2816, s15
	s_cselect_b32 s19, 0, 1
	s_sub_u32 s15, s0, s15
	s_lshr_b32 s16, s15, 4
	s_and_b32 s17, s15, 15
	s_cmp_eq_u32 s19, 0
	s_movk_i32 s10, 0x800
	s_cselect_b32 s10, 0x1600, s10
	s_mov_b32 s18, 0x1780000
	s_cselect_b32 s18, 0x1200000, s18
	s_mov_b32 s14, s19
	s_lshl_b32 s15, s17, 6
	s_mul_i32 s15, s15, s10
	s_lshl_b32 s16, s16, 6
	s_add_u32 s15, s15, s16
	s_add_u32 s15, s15, s18
	s_add_u32 s8, s24, s15
	s_addc_u32 s9, s25, 0
.Ltp44_end:
	s_cmp_eq_u32 s14, 0
	s_cbranch_scc0 .Ltp45_g
	v_mov_b32_e32 v48, 1.0
	v_mov_b32_e32 v49, 1.0
	v_mov_b32_e32 v50, 1.0
	v_mov_b32_e32 v51, 1.0
	v_mov_b32_e32 v52, 1.0
	v_mov_b32_e32 v53, 1.0
	v_mov_b32_e32 v54, 1.0
	v_mov_b32_e32 v55, 1.0
.Ltp45_g:
	v_mad_u32_u24 v5, v2, s10, v6
	v_mul_f32_e32 v16, v16, v48
	v_mul_f32_e32 v17, v17, v48
	v_mul_f32_e32 v18, v18, v48
	v_mul_f32_e32 v19, v19, v48
	v_mul_f32_e32 v20, v20, v49
	v_mul_f32_e32 v21, v21, v49
	v_mul_f32_e32 v22, v22, v49
	v_mul_f32_e32 v23, v23, v49
	v_mul_f32_e32 v24, v24, v50
	v_mul_f32_e32 v25, v25, v50
	v_mul_f32_e32 v26, v26, v50
	v_mul_f32_e32 v27, v27, v50
	v_mul_f32_e32 v28, v28, v51
	v_mul_f32_e32 v29, v29, v51
	v_mul_f32_e32 v30, v30, v51
	v_mul_f32_e32 v31, v31, v51
	v_mul_f32_e32 v32, v32, v52
	v_mul_f32_e32 v33, v33, v52
	v_mul_f32_e32 v34, v34, v52
	v_mul_f32_e32 v35, v35, v52
	v_mul_f32_e32 v36, v36, v53
	v_mul_f32_e32 v37, v37, v53
	v_mul_f32_e32 v38, v38, v53
	v_mul_f32_e32 v39, v39, v53
	v_mul_f32_e32 v40, v40, v54
	v_mul_f32_e32 v41, v41, v54
	v_mul_f32_e32 v42, v42, v54
	v_mul_f32_e32 v43, v43, v54
	v_mul_f32_e32 v44, v44, v55
	v_mul_f32_e32 v45, v45, v55
	v_mul_f32_e32 v46, v46, v55
	v_mul_f32_e32 v47, v47, v55
	v_cvt_pk_bf16_f32 v136, v16, v20
	v_cvt_pk_bf16_f32 v137, v24, v28
	v_cvt_pk_bf16_f32 v138, v32, v36
	v_cvt_pk_bf16_f32 v139, v40, v44
	v_cvt_pk_bf16_f32 v140, v17, v21
	v_cvt_pk_bf16_f32 v141, v25, v29
	v_cvt_pk_bf16_f32 v142, v33, v37
	v_cvt_pk_bf16_f32 v143, v41, v45
	v_cvt_pk_bf16_f32 v144, v18, v22
	v_cvt_pk_bf16_f32 v145, v26, v30
	v_cvt_pk_bf16_f32 v146, v34, v38
	v_cvt_pk_bf16_f32 v147, v42, v46
	v_cvt_pk_bf16_f32 v148, v19, v23
	v_cvt_pk_bf16_f32 v149, v27, v31
	v_cvt_pk_bf16_f32 v150, v35, v39
	v_cvt_pk_bf16_f32 v151, v43, v47
	global_store_dwordx4 v5, v[136:139], s[8:9]
	s_add_u32 s8, s8, s10
	s_addc_u32 s9, s9, 0
	global_store_dwordx4 v5, v[140:143], s[8:9]
	s_add_u32 s8, s8, s10
	s_addc_u32 s9, s9, 0
	global_store_dwordx4 v5, v[144:147], s[8:9]
	s_add_u32 s8, s8, s10
	s_addc_u32 s9, s9, 0
	global_store_dwordx4 v5, v[148:151], s[8:9]
	s_add_u32 s11, s0, s1
	s_cmp_lt_u32 s11, 4736
	s_cbranch_scc0 .Ltp4_done
	s_waitcnt vmcnt(14)
	s_cmp_lt_u32 s2, 2816
	s_cbranch_scc0 .Ltp46_hi
	s_cmp_lt_u32 s2, 1408
	s_cselect_b32 s15, 0, 1408
	s_cselect_b32 s19, 0, 1
	s_sub_u32 s15, s2, s15
	s_mul_hi_u32 s16, s15, 0x5d1745e
	s_mul_i32 s17, s16, 44
	s_sub_u32 s17, s15, s17
	s_lshr_b32 s15, s17, 1
	s_lshl_b32 s15, s15, 8
	s_and_b32 s18, s17, 1
	s_lshl_b32 s18, s18, 6
	s_add_u32 s15, s15, s18
	s_lshl_b32 s18, s19, 7
	s_add_u32 s15, s15, s18
	s_lshl_b32 s15, s15, 11
	s_lshl_b32 s18, s16, 6
	s_add_u32 s15, s15, s18
	s_add_u32 s15, s15, 0x700000
	s_add_u32 s8, s24, s15
	s_addc_u32 s9, s25, 0
	s_movk_i32 s10, 0x800
	s_mov_b32 s14, 1
	s_branch .Ltp46_end
.Ltp46_hi:
	s_cmp_lt_u32 s2, 4224
	s_mov_b32 s15, 4224
	s_cselect_b32 s15, 2816, s15
	s_cselect_b32 s19, 0, 1
	s_sub_u32 s15, s2, s15
	s_lshr_b32 s16, s15, 4
	s_and_b32 s17, s15, 15
	s_cmp_eq_u32 s19, 0
	s_movk_i32 s10, 0x800
	s_cselect_b32 s10, 0x1600, s10
	s_mov_b32 s18, 0x1780000
	s_cselect_b32 s18, 0x1200000, s18
	s_mov_b32 s14, s19
	s_lshl_b32 s15, s17, 6
	s_mul_i32 s15, s15, s10
	s_lshl_b32 s16, s16, 6
	s_add_u32 s15, s15, s16
	s_add_u32 s15, s15, s18
	s_add_u32 s8, s24, s15
	s_addc_u32 s9, s25, 0
.Ltp46_end:
	s_cmp_eq_u32 s14, 0
	s_cbranch_scc0 .Ltp47_g
	v_mov_b32_e32 v88, 1.0
	v_mov_b32_e32 v89, 1.0
	v_mov_b32_e32 v90, 1.0
	v_mov_b32_e32 v91, 1.0
	v_mov_b32_e32 v92, 1.0
	v_mov_b32_e32 v93, 1.0
	v_mov_b32_e32 v94, 1.0
	v_mov_b32_e32 v95, 1.0
.Ltp47_g:
	v_mad_u32_u24 v5, v2, s10, v6
	v_mul_f32_e32 v56, v56, v88
	v_mul_f32_e32 v57, v57, v88
	v_mul_f32_e32 v58, v58, v88
	v_mul_f32_e32 v59, v59, v88
	v_mul_f32_e32 v60, v60, v89
	v_mul_f32_e32 v61, v61, v89
	v_mul_f32_e32 v62, v62, v89
	v_mul_f32_e32 v63, v63, v89
	v_mul_f32_e32 v64, v64, v90
	v_mul_f32_e32 v65, v65, v90
	v_mul_f32_e32 v66, v66, v90
	v_mul_f32_e32 v67, v67, v90
	v_mul_f32_e32 v68, v68, v91
	v_mul_f32_e32 v69, v69, v91
	v_mul_f32_e32 v70, v70, v91
	v_mul_f32_e32 v71, v71, v91
	v_mul_f32_e32 v72, v72, v92
	v_mul_f32_e32 v73, v73, v92
	v_mul_f32_e32 v74, v74, v92
	v_mul_f32_e32 v75, v75, v92
	v_mul_f32_e32 v76, v76, v93
	v_mul_f32_e32 v77, v77, v93
	v_mul_f32_e32 v78, v78, v93
	v_mul_f32_e32 v79, v79, v93
	v_mul_f32_e32 v80, v80, v94
	v_mul_f32_e32 v81, v81, v94
	v_mul_f32_e32 v82, v82, v94
	v_mul_f32_e32 v83, v83, v94
	v_mul_f32_e32 v84, v84, v95
	v_mul_f32_e32 v85, v85, v95
	v_mul_f32_e32 v86, v86, v95
	v_mul_f32_e32 v87, v87, v95
	v_cvt_pk_bf16_f32 v136, v56, v60
	v_cvt_pk_bf16_f32 v137, v64, v68
	v_cvt_pk_bf16_f32 v138, v72, v76
	v_cvt_pk_bf16_f32 v139, v80, v84
	v_cvt_pk_bf16_f32 v140, v57, v61
	v_cvt_pk_bf16_f32 v141, v65, v69
	v_cvt_pk_bf16_f32 v142, v73, v77
	v_cvt_pk_bf16_f32 v143, v81, v85
	v_cvt_pk_bf16_f32 v144, v58, v62
	v_cvt_pk_bf16_f32 v145, v66, v70
	v_cvt_pk_bf16_f32 v146, v74, v78
	v_cvt_pk_bf16_f32 v147, v82, v86
	v_cvt_pk_bf16_f32 v148, v59, v63
	v_cvt_pk_bf16_f32 v149, v67, v71
	v_cvt_pk_bf16_f32 v150, v75, v79
	v_cvt_pk_bf16_f32 v151, v83, v87
	global_store_dwordx4 v5, v[136:139], s[8:9]
	s_add_u32 s8, s8, s10
	s_addc_u32 s9, s9, 0
	global_store_dwordx4 v5, v[140:143], s[8:9]
	s_add_u32 s8, s8, s10
	s_addc_u32 s9, s9, 0
	global_store_dwordx4 v5, v[144:147], s[8:9]
	s_add_u32 s8, s8, s10
	s_addc_u32 s9, s9, 0
	global_store_dwordx4 v5, v[148:151], s[8:9]
	s_add_u32 s11, s11, s1
	s_cmp_lt_u32 s11, 4736
	s_cbranch_scc0 .Ltp4_done
	s_waitcnt vmcnt(8)
	s_cmp_lt_u32 s3, 2816
	s_cbranch_scc0 .Ltp48_hi
	s_cmp_lt_u32 s3, 1408
	s_cselect_b32 s15, 0, 1408
	s_cselect_b32 s19, 0, 1
	s_sub_u32 s15, s3, s15
	s_mul_hi_u32 s16, s15, 0x5d1745e
	s_mul_i32 s17, s16, 44
	s_sub_u32 s17, s15, s17
	s_lshr_b32 s15, s17, 1
	s_lshl_b32 s15, s15, 8
	s_and_b32 s18, s17, 1
	s_lshl_b32 s18, s18, 6
	s_add_u32 s15, s15, s18
	s_lshl_b32 s18, s19, 7
	s_add_u32 s15, s15, s18
	s_lshl_b32 s15, s15, 11
	s_lshl_b32 s18, s16, 6
	s_add_u32 s15, s15, s18
	s_add_u32 s15, s15, 0x700000
	s_add_u32 s8, s24, s15
	s_addc_u32 s9, s25, 0
	s_movk_i32 s10, 0x800
	s_mov_b32 s14, 1
	s_branch .Ltp48_end
.Ltp48_hi:
	s_cmp_lt_u32 s3, 4224
	s_mov_b32 s15, 4224
	s_cselect_b32 s15, 2816, s15
	s_cselect_b32 s19, 0, 1
	s_sub_u32 s15, s3, s15
	s_lshr_b32 s16, s15, 4
	s_and_b32 s17, s15, 15
	s_cmp_eq_u32 s19, 0
	s_movk_i32 s10, 0x800
	s_cselect_b32 s10, 0x1600, s10
	s_mov_b32 s18, 0x1780000
	s_cselect_b32 s18, 0x1200000, s18
	s_mov_b32 s14, s19
	s_lshl_b32 s15, s17, 6
	s_mul_i32 s15, s15, s10
	s_lshl_b32 s16, s16, 6
	s_add_u32 s15, s15, s16
	s_add_u32 s15, s15, s18
	s_add_u32 s8, s24, s15
	s_addc_u32 s9, s25, 0
.Ltp48_end:
	s_cmp_eq_u32 s14, 0
	s_cbranch_scc0 .Ltp49_g
	v_mov_b32_e32 v128, 1.0
	v_mov_b32_e32 v129, 1.0
	v_mov_b32_e32 v130, 1.0
	v_mov_b32_e32 v131, 1.0
	v_mov_b32_e32 v132, 1.0
	v_mov_b32_e32 v133, 1.0
	v_mov_b32_e32 v134, 1.0
	v_mov_b32_e32 v135, 1.0
.Ltp49_g:
	v_mad_u32_u24 v5, v2, s10, v6
	v_mul_f32_e32 v96, v96, v128
	v_mul_f32_e32 v97, v97, v128
	v_mul_f32_e32 v98, v98, v128
	v_mul_f32_e32 v99, v99, v128
	v_mul_f32_e32 v100, v100, v129
	v_mul_f32_e32 v101, v101, v129
	v_mul_f32_e32 v102, v102, v129
	v_mul_f32_e32 v103, v103, v129
	v_mul_f32_e32 v104, v104, v130
	v_mul_f32_e32 v105, v105, v130
	v_mul_f32_e32 v106, v106, v130
	v_mul_f32_e32 v107, v107, v130
	v_mul_f32_e32 v108, v108, v131
	v_mul_f32_e32 v109, v109, v131
	v_mul_f32_e32 v110, v110, v131
	v_mul_f32_e32 v111, v111, v131
	v_mul_f32_e32 v112, v112, v132
	v_mul_f32_e32 v113, v113, v132
	v_mul_f32_e32 v114, v114, v132
	v_mul_f32_e32 v115, v115, v132
	v_mul_f32_e32 v116, v116, v133
	v_mul_f32_e32 v117, v117, v133
	v_mul_f32_e32 v118, v118, v133
	v_mul_f32_e32 v119, v119, v133
	v_mul_f32_e32 v120, v120, v134
	v_mul_f32_e32 v121, v121, v134
	v_mul_f32_e32 v122, v122, v134
	v_mul_f32_e32 v123, v123, v134
	v_mul_f32_e32 v124, v124, v135
	v_mul_f32_e32 v125, v125, v135
	v_mul_f32_e32 v126, v126, v135
	v_mul_f32_e32 v127, v127, v135
	v_cvt_pk_bf16_f32 v136, v96, v100
	v_cvt_pk_bf16_f32 v137, v104, v108
	v_cvt_pk_bf16_f32 v138, v112, v116
	v_cvt_pk_bf16_f32 v139, v120, v124
	v_cvt_pk_bf16_f32 v140, v97, v101
	v_cvt_pk_bf16_f32 v141, v105, v109
	v_cvt_pk_bf16_f32 v142, v113, v117
	v_cvt_pk_bf16_f32 v143, v121, v125
	v_cvt_pk_bf16_f32 v144, v98, v102
	v_cvt_pk_bf16_f32 v145, v106, v110
	v_cvt_pk_bf16_f32 v146, v114, v118
	v_cvt_pk_bf16_f32 v147, v122, v126
	v_cvt_pk_bf16_f32 v148, v99, v103
	v_cvt_pk_bf16_f32 v149, v107, v111
	v_cvt_pk_bf16_f32 v150, v115, v119
	v_cvt_pk_bf16_f32 v151, v123, v127
	global_store_dwordx4 v5, v[136:139], s[8:9]
	s_add_u32 s8, s8, s10
	s_addc_u32 s9, s9, 0
	global_store_dwordx4 v5, v[140:143], s[8:9]
	s_add_u32 s8, s8, s10
	s_addc_u32 s9, s9, 0
	global_store_dwordx4 v5, v[144:147], s[8:9]
	s_add_u32 s8, s8, s10
	s_addc_u32 s9, s9, 0
	global_store_dwordx4 v5, v[148:151], s[8:9]
	s_add_u32 s0, s11, s1
	s_branch .Ltp4_loop
.Ltp4_done:
	v_readlane_b32 s0, v251, 0
	v_readlane_b32 s1, v251, 1
	v_readlane_b32 s2, v251, 2
	v_readlane_b32 s3, v251, 3
	v_readlane_b32 s4, v251, 4
	v_readlane_b32 s5, v251, 5
	v_readlane_b32 s6, v251, 6
	v_readlane_b32 s7, v251, 7
	v_readlane_b32 s8, v251, 8
	v_readlane_b32 s9, v251, 9
	v_readlane_b32 s10, v251, 10
	v_readlane_b32 s11, v251, 11
	v_readlane_b32 s12, v251, 12
	v_readlane_b32 s13, v251, 13
	v_readlane_b32 s14, v251, 14
	v_readlane_b32 s15, v251, 15
	v_readlane_b32 s16, v251, 16
	v_readlane_b32 s17, v251, 17
	v_readlane_b32 s18, v251, 18
	v_readlane_b32 s19, v251, 19
	s_nop 1

	.amdhsa_kernel _Z14fwd_megakernel6Params
		.amdhsa_group_segment_fixed_size 0
		.amdhsa_private_segment_fixed_size 0
		.amdhsa_kernarg_size 512
		.amdhsa_user_sgpr_count 2
		.amdhsa_user_sgpr_dispatch_ptr 0
		.amdhsa_user_sgpr_queue_ptr 0
		.amdhsa_user_sgpr_kernarg_segment_ptr 1
		.amdhsa_user_sgpr_dispatch_id 0
		.amdhsa_user_sgpr_kernarg_preload_length 0
		.amdhsa_user_sgpr_kernarg_preload_offset 0
		.amdhsa_user_sgpr_private_segment_size 0
		.amdhsa_uses_dynamic_stack 0
		.amdhsa_enable_private_segment 0
		.amdhsa_system_sgpr_workgroup_id_x 1
		.amdhsa_system_sgpr_workgroup_id_y 0
		.amdhsa_system_sgpr_workgroup_id_z 0
		.amdhsa_system_sgpr_workgroup_info 0
		.amdhsa_system_vgpr_workitem_id 2
		.amdhsa_next_free_vgpr 256
		.amdhsa_next_free_sgpr 98
		.amdhsa_accum_offset 256
		.amdhsa_reserve_vcc 1
		.amdhsa_float_round_mode_32 0
		.amdhsa_float_round_mode_16_64 0
		.amdhsa_float_denorm_mode_32 3
		.amdhsa_float_denorm_mode_16_64 3
		.amdhsa_dx10_clamp 1
		.amdhsa_ieee_mode 1
		.amdhsa_fp16_overflow 0
		.amdhsa_tg_split 0
		.amdhsa_exception_fp_ieee_invalid_op 0
		.amdhsa_exception_fp_denorm_src 0
		.amdhsa_exception_fp_ieee_div_zero 0
		.amdhsa_exception_fp_ieee_overflow 0
		.amdhsa_exception_fp_ieee_underflow 0
		.amdhsa_exception_fp_ieee_inexact 0
		.amdhsa_exception_int_div_zero 0
	.end_amdhsa_kernel

amdhsa.kernels:
  - .agpr_count:     0
    .args:
      - .offset:         0
        .size:           256
        .value_kind:     by_value
      - .offset:         256
        .size:           4
        .value_kind:     hidden_block_count_x
      - .offset:         260
        .size:           4
        .value_kind:     hidden_block_count_y
      - .offset:         264
        .size:           4
        .value_kind:     hidden_block_count_z
      - .offset:         268
        .size:           2
        .value_kind:     hidden_group_size_x
      - .offset:         270
        .size:           2
        .value_kind:     hidden_group_size_y
      - .offset:         272
        .size:           2
        .value_kind:     hidden_group_size_z
      - .offset:         274
        .size:           2
        .value_kind:     hidden_remainder_x
      - .offset:         276
        .size:           2
        .value_kind:     hidden_remainder_y
      - .offset:         278
        .size:           2
        .value_kind:     hidden_remainder_z
      - .offset:         296
        .size:           8
        .value_kind:     hidden_global_offset_x
      - .offset:         304
        .size:           8
        .value_kind:     hidden_global_offset_y
      - .offset:         312
        .size:           8
        .value_kind:     hidden_global_offset_z
      - .offset:         320
        .size:           2
        .value_kind:     hidden_grid_dims
      - .offset:         344
        .size:           8
        .value_kind:     hidden_multigrid_sync_arg
      - .offset:         376
        .size:           4
        .value_kind:     hidden_dynamic_lds_size
    .group_segment_fixed_size: 0
    .kernarg_segment_align: 8
    .kernarg_segment_size: 512
    .language:       OpenCL C
    .language_version:
      - 2
      - 0
    .max_flat_workgroup_size: 512
    .name:           _Z14fwd_megakernel6Params
    .private_segment_fixed_size: 0
    .sgpr_count:     104
    .sgpr_spill_count: 106
    .symbol:         _Z14fwd_megakernel6Params.kd
    .uniform_work_group_size: 1
    .uses_dynamic_stack: false
    .vgpr_count: 256
    .vgpr_spill_count: 0
    .wavefront_size: 64
